# final stack plus non-temporal hint on P16's y output stores (71 MB written once, never re-read by the kernel)
# speedup vs baseline: 1.0074x; 1.0053x over previous
; #define GAS __attribute__((address_space(1)))
;     ...
;             ss = wave_sum(ss);
;             const float rs = sc * (1.0f / sqrtf(ss * (1.0f / D) + EPS));
; #pragma unroll
;             for (int j = 0; j < 8; ++j) { const f32x4 g = gpo[j]; v[j] = v[j] + (t[j] * rs) * g;
;                 if (MODE == 2) ((GAS f32x4*)(Yout + (size_t)r * D))[lane + 64 * j] = v[j];
.LBB0_1898:
	ds_bpermute_b32 v91, v92, v90
	s_waitcnt vmcnt(0)
	v_and_b32_e32 v117, 0xffff0000, v76
	v_and_b32_e32 v115, 0xffff0000, v78
	v_lshlrev_b32_e32 v106, 16, v88
	v_and_b32_e32 v107, 0xffff0000, v88
	s_waitcnt lgkmcnt(0)
	v_add_f32_e32 v105, v90, v91
	ds_bpermute_b32 v110, v93, v105
	v_lshlrev_b32_e32 v88, 16, v89
	v_and_b32_e32 v89, 0xffff0000, v89
	v_lshlrev_b32_e32 v108, 16, v86
	v_and_b32_e32 v109, 0xffff0000, v86
	s_waitcnt lgkmcnt(0)
	v_add_f32_e32 v105, v105, v110
	ds_bpermute_b32 v112, v94, v105
	v_lshlrev_b32_e32 v86, 16, v87
	v_and_b32_e32 v87, 0xffff0000, v87
	v_lshlrev_b32_e32 v90, 16, v84
	v_and_b32_e32 v91, 0xffff0000, v84
	s_waitcnt lgkmcnt(0)
	v_add_f32_e32 v105, v105, v112
	ds_bpermute_b32 v114, v95, v105
	v_lshlrev_b32_e32 v84, 16, v85
	v_and_b32_e32 v85, 0xffff0000, v85
	v_lshlrev_b32_e32 v110, 16, v82
	v_and_b32_e32 v111, 0xffff0000, v82
	s_waitcnt lgkmcnt(0)
	v_add_f32_e32 v105, v105, v114
	ds_bpermute_b32 v116, v96, v105
	v_lshlrev_b32_e32 v114, 16, v78
	v_lshlrev_b32_e32 v78, 16, v79
	v_and_b32_e32 v79, 0xffff0000, v79
	v_lshlrev_b32_e32 v82, 16, v83
	s_waitcnt lgkmcnt(0)
	v_add_f32_e32 v105, v105, v116
	ds_bpermute_b32 v118, v97, v105
	v_lshlrev_b32_e32 v116, 16, v76
	v_and_b32_e32 v83, 0xffff0000, v83
	v_lshlrev_b32_e32 v112, 16, v80
	v_and_b32_e32 v113, 0xffff0000, v80
	s_waitcnt lgkmcnt(0)
	v_add_f32_e32 v76, v105, v118
	v_fmamk_f32 v76, v76, 0x3a000000, v98
	v_mul_f32_e32 v105, 0x4f800000, v76
	v_cmp_gt_f32_e32 vcc, s11, v76
	v_lshlrev_b32_e32 v80, 16, v81
	v_and_b32_e32 v81, 0xffff0000, v81
	v_cndmask_b32_e32 v105, v76, v105, vcc
	v_sqrt_f32_e32 v119, v105
	v_lshlrev_b32_e32 v76, 16, v77
	v_and_b32_e32 v77, 0xffff0000, v77
	v_lshlrev_b32_e32 v118, 16, v74
	v_add_u32_e32 v120, -1, v119
	v_fma_f32 v121, -v120, v119, v105
	v_cmp_ge_f32_e64 s[0:1], 0, v121
	v_add_u32_e32 v121, 1, v119
	s_nop 0
	v_cndmask_b32_e64 v120, v119, v120, s[0:1]
	v_fma_f32 v119, -v121, v119, v105
	v_cmp_lt_f32_e64 s[0:1], 0, v119
	s_nop 1
	v_cndmask_b32_e64 v119, v120, v121, s[0:1]
	v_mul_f32_e32 v120, 0x37800000, v119
	v_cndmask_b32_e32 v119, v119, v120, vcc
	v_cmp_class_f32_e32 vcc, v105, v99
	s_nop 1
	v_cndmask_b32_e32 v105, v119, v105, vcc
	v_div_scale_f32 v120, s[0:1], v105, v105, 1.0
	v_rcp_f32_e32 v121, v120
	s_lshl_b64 s[0:1], s[6:7], 2
	s_add_u32 s0, s90, s0
	s_addc_u32 s1, s91, s1
	v_fma_f32 v122, -v120, v121, 1.0
	v_fmac_f32_e32 v121, v122, v121
	v_div_scale_f32 v122, vcc, 1.0, v105, 1.0
	v_mul_f32_e32 v123, v122, v121
	v_fma_f32 v124, -v120, v123, v122
	v_fmac_f32_e32 v123, v124, v121
	v_fma_f32 v120, -v120, v123, v122
	v_div_fmas_f32 v120, v120, v121, v123
	v_div_fixup_f32 v120, v120, v105, 1.0
	v_pk_mul_f32 v[40:41], v[40:41], v[120:121] op_sel_hi:[1,0]
	v_pk_mul_f32 v[42:43], v[42:43], v[120:121] op_sel_hi:[1,0]
	v_pk_mul_f32 v[122:123], v[60:61], v[120:121] op_sel_hi:[1,0]
	v_pk_mul_f32 v[58:59], v[58:59], v[120:121] op_sel_hi:[1,0]
	v_pk_fma_f32 v[42:43], v[22:23], v[42:43], v[78:79]
	v_pk_fma_f32 v[40:41], v[20:21], v[40:41], v[114:115]
	v_pk_fma_f32 v[60:61], v[2:3], v[58:59], v[88:89]
	v_pk_fma_f32 v[58:59], v[0:1], v[122:123], v[106:107]
	global_store_dwordx4 v102, v[40:43], s[0:1] nt
	v_pk_mul_f32 v[36:37], v[36:37], v[120:121] op_sel_hi:[1,0]
	global_store_dwordx4 v100, v[58:61], s[0:1] nt
	v_pk_mul_f32 v[40:41], v[38:39], v[120:121] op_sel_hi:[1,0]
	v_pk_mul_f32 v[54:55], v[54:55], v[120:121] op_sel_hi:[1,0]
	v_pk_mul_f32 v[58:59], v[62:63], v[120:121] op_sel_hi:[1,0]
	v_pk_mul_f32 v[48:49], v[48:49], v[120:121] op_sel_hi:[1,0]
	v_pk_fma_f32 v[38:39], v[26:27], v[36:37], v[76:77]
	v_pk_fma_f32 v[36:37], v[24:25], v[40:41], v[116:117]
	v_and_b32_e32 v119, 0xffff0000, v74
	v_lshlrev_b32_e32 v74, 16, v75
	v_and_b32_e32 v75, 0xffff0000, v75
	v_pk_fma_f32 v[60:61], v[6:7], v[58:59], v[86:87]
	v_pk_fma_f32 v[58:59], v[4:5], v[54:55], v[108:109]
	v_pk_mul_f32 v[52:53], v[52:53], v[120:121] op_sel_hi:[1,0]
	v_pk_fma_f32 v[54:55], v[10:11], v[48:49], v[84:85]
	v_pk_mul_f32 v[48:49], v[56:57], v[120:121] op_sel_hi:[1,0]
	v_pk_mul_f32 v[50:51], v[50:51], v[120:121] op_sel_hi:[1,0]
	v_pk_mul_f32 v[44:45], v[44:45], v[120:121] op_sel_hi:[1,0]
	v_pk_mul_f32 v[46:47], v[46:47], v[120:121] op_sel_hi:[1,0]
	global_store_dwordx4 v103, v[36:39], s[0:1] nt
	v_pk_mul_f32 v[32:33], v[32:33], v[120:121] op_sel_hi:[1,0]
	s_add_i32 s2, s2, s8
	v_pk_mul_f32 v[36:37], v[34:35], v[120:121] op_sel_hi:[1,0]
	s_add_i32 s4, s4, s8
	v_pk_fma_f32 v[52:53], v[8:9], v[52:53], v[90:91]
	v_pk_fma_f32 v[50:51], v[14:15], v[50:51], v[82:83]
	v_pk_fma_f32 v[48:49], v[12:13], v[48:49], v[110:111]
	v_pk_fma_f32 v[46:47], v[18:19], v[46:47], v[80:81]
	v_pk_fma_f32 v[44:45], v[16:17], v[44:45], v[112:113]
	v_pk_fma_f32 v[34:35], v[30:31], v[32:33], v[74:75]
	v_pk_fma_f32 v[32:33], v[28:29], v[36:37], v[118:119]
	s_cmpk_lt_i32 s2, 0x2200
	global_store_dwordx4 v100, v[58:61], s[0:1] offset:1024 nt
	global_store_dwordx4 v100, v[52:55], s[0:1] offset:2048 nt
	global_store_dwordx4 v100, v[48:51], s[0:1] offset:3072 nt
	global_store_dwordx4 v101, v[44:47], s[0:1] nt
	global_store_dwordx4 v104, v[32:35], s[0:1] nt
	s_cbranch_scc0 .LBB0_1905
